# v21 + mode-1 GEMM epilogue residual loads software-pipelined (4 row-pairs in flight instead of 1)
# speedup vs baseline: 1.0038x; 1.0038x over previous
; template <int MODE> DI void epilogue(const Epi& E, f32x4 (&acc)[2][2][4][2], const Unit& u, int wr, int wc, int fr, int fq) {
;     ...
;     } else if constexpr (emode == 1) {
;         const int bidx = batch_of_row(u.pm * BM);
;         const char* base = (const char*)((u.pm * BM < TP) ? E.base_p : E.base_s);
;         const int col0 = u.pn * BM + wc * 64 + 8 * fq;
;         const unsigned ro = ((unsigned)row0 * D + (unsigned)col0) * 4u;
;     ...
; #pragma unroll
;         for (int bj = 0; bj < 2; ++bj) {
;             const f32x4 g0 = *(const f32x4*)(E.gt + bidx * 6144 + col0 + bj * 32), g1 = *(const f32x4*)(E.gt + bidx * 6144 + col0 + bj * 32 + 4);
; #pragma unroll
;             for (int ai = 0; ai < 2; ++ai)
; #pragma unroll
;                 for (int m = 0; m < 4; ++m) {
;                     const unsigned off = E1_OFF(ai, m, bj);
;                     const f32x4 b0 = __builtin_nontemporal_load((const f32x4*)(base + off)), b1 = __builtin_nontemporal_load((const f32x4*)(base + off + 16));
;                     acc[ai][bj][m][0] = b0 + g0 * acc[ai][bj][m][0];
;                     acc[ai][bj][m][1] = b1 + g1 * acc[ai][bj][m][1];
;                     asm volatile("" : "+v"(acc[ai][bj][m][0]), "+v"(acc[ai][bj][m][1]));
;                 }
.LBB0_502:
	s_lshl_b32 s3, s8, 8
	v_add_u32_e32 v184, s3, v196
	s_add_i32 s3, s3, 0xffff0000
	s_lshr_b32 s3, s3, 12
	s_lshr_b32 s9, s8, 5
	s_add_i32 s3, s3, 8
	v_readlane_b32 s60, v254, 22
	s_cmpk_lt_i32 s8, 0x100
	v_readlane_b32 s61, v254, 23
	s_cselect_b32 s3, s9, s3
	s_mov_b64 s[8:9], s[60:61]
	v_readlane_b32 s25, v254, 58
	s_cselect_b32 s9, s9, s25
	v_readlane_b32 s25, v254, 56
	v_lshl_or_b32 v182, s2, 8, v198
	s_mul_i32 s2, s3, 0x1800
	s_cselect_b32 s8, s8, s25
	s_ashr_i32 s3, s2, 31
	s_lshl_b64 s[2:3], s[2:3], 2
	s_add_u32 s34, s47, s2
	v_lshlrev_b32_e32 v128, 2, v182
	v_ashrrev_i32_e32 v183, 31, v182
	s_addc_u32 s35, s48, s3
	v_lshl_add_u32 v144, v184, 12, v128
	v_lshl_add_u64 v[128:129], v[182:183], 2, s[34:35]
	global_load_dwordx4 v[130:133], v[128:129], off
	global_load_dwordx4 v[178:181], v[128:129], off offset:16
	global_load_dwordx4 v[186:189], v144, s[8:9] nt
	global_load_dwordx4 v[208:211], v144, s[8:9] offset:16 nt
	v_add_u32_e32 v175, 0x10000, v144
	global_load_dwordx4 v[212:215], v175, s[8:9] nt
	global_load_dwordx4 v[216:219], v175, s[8:9] offset:16 nt
	v_add_u32_e32 v173, 0x20000, v144
	global_load_dwordx4 v[220:223], v173, s[8:9] nt
	global_load_dwordx4 v[224:227], v173, s[8:9] offset:16 nt
	v_add_u32_e32 v175, 0x30000, v144
	global_load_dwordx4 v[240:243], v175, s[8:9] nt
	global_load_dwordx4 v[244:247], v175, s[8:9] offset:16 nt
	v_add_u32_e32 v166, 0x10000, v144
	v_add_u32_e32 v172, 0x20000, v144
	v_add_u32_e32 v176, 0x30000, v144
	v_add_u32_e32 v174, 0x90080, v144
	v_ashrrev_i32_e32 v185, 31, v184
	v_readlane_b32 s62, v254, 24
	v_readlane_b32 s63, v254, 25
	v_readlane_b32 s64, v254, 26
	v_readlane_b32 s65, v254, 27
	v_readlane_b32 s66, v254, 28
	v_readlane_b32 s67, v254, 29
	v_readlane_b32 s68, v254, 30
	v_readlane_b32 s69, v254, 31
	v_readlane_b32 s70, v254, 32
	v_readlane_b32 s71, v254, 33
	v_readlane_b32 s72, v254, 34
	v_readlane_b32 s73, v254, 35
	v_readlane_b32 s74, v254, 36
	v_readlane_b32 s75, v254, 37
	s_waitcnt vmcnt(7)
	v_pk_fma_f32 v[50:51], v[50:51], v[132:133], v[188:189]
	v_pk_fma_f32 v[48:49], v[48:49], v[130:131], v[186:187]
	s_waitcnt vmcnt(6)
	v_pk_fma_f32 v[30:31], v[30:31], v[180:181], v[210:211]
	v_pk_fma_f32 v[28:29], v[28:29], v[178:179], v[208:209]
	v_add_u32_e32 v173, 0x80000, v144
	global_load_dwordx4 v[186:189], v173, s[8:9] nt
	global_load_dwordx4 v[208:211], v173, s[8:9] offset:16 nt
	s_nop 0
	s_waitcnt vmcnt(7)
	v_pk_fma_f32 v[70:71], v[70:71], v[132:133], v[214:215]
	v_pk_fma_f32 v[68:69], v[68:69], v[130:131], v[212:213]
	s_waitcnt vmcnt(6)
	v_pk_fma_f32 v[54:55], v[54:55], v[180:181], v[218:219]
	v_pk_fma_f32 v[52:53], v[52:53], v[178:179], v[216:217]
	v_add_u32_e32 v175, 0x90000, v144
	global_load_dwordx4 v[212:215], v175, s[8:9] nt
	global_load_dwordx4 v[216:219], v175, s[8:9] offset:16 nt
	s_nop 0
	s_waitcnt vmcnt(7)
	v_pk_fma_f32 v[86:87], v[86:87], v[132:133], v[222:223]
	v_pk_fma_f32 v[84:85], v[84:85], v[130:131], v[220:221]
	s_waitcnt vmcnt(6)
	v_pk_fma_f32 v[78:79], v[78:79], v[180:181], v[226:227]
	v_pk_fma_f32 v[76:77], v[76:77], v[178:179], v[224:225]
	v_add_u32_e32 v173, 0xa0000, v144
	global_load_dwordx4 v[220:223], v173, s[8:9] nt
	global_load_dwordx4 v[224:227], v173, s[8:9] offset:16 nt
	v_add_u32_e32 v156, 0x80000, v144
	v_add_u32_e32 v154, 0x10080, v144
	v_and_b32_e32 v157, 64, v202
	v_xor_b32_e32 v155, 16, v202
	v_add_u32_e32 v157, 64, v157
	v_cmp_lt_i32_e32 vcc, v155, v157
	s_waitcnt vmcnt(7)
	v_pk_fma_f32 v[98:99], v[98:99], v[132:133], v[242:243]
	v_pk_fma_f32 v[96:97], v[96:97], v[130:131], v[240:241]
	s_waitcnt vmcnt(6)
	v_pk_fma_f32 v[90:91], v[90:91], v[180:181], v[246:247]
	v_pk_fma_f32 v[88:89], v[88:89], v[178:179], v[244:245]
	v_add_u32_e32 v175, 0xb0000, v144
	global_load_dwordx4 v[240:243], v175, s[8:9] nt
	global_load_dwordx4 v[244:247], v175, s[8:9] offset:16 nt
	v_add_u32_e32 v160, 0x90000, v144
	v_add_u32_e32 v158, 0x20080, v144
	v_mul_f32_e32 v159, v49, v49
	v_mul_f32_e32 v161, v51, v51
	v_fmac_f32_e32 v159, v48, v48
	v_fmac_f32_e32 v161, v50, v50
	v_add_f32_e32 v159, v159, v161
	v_cndmask_b32_e32 v155, v202, v155, vcc
	v_lshlrev_b32_e32 v155, 2, v155
	s_waitcnt vmcnt(7)
	v_pk_fma_f32 v[114:115], v[114:115], v[132:133], v[188:189]
	v_pk_fma_f32 v[112:113], v[112:113], v[130:131], v[186:187]
	s_waitcnt vmcnt(6)
	v_pk_fma_f32 v[106:107], v[106:107], v[180:181], v[210:211]
	v_pk_fma_f32 v[104:105], v[104:105], v[178:179], v[208:209]
	global_load_dwordx4 v[186:189], v144, s[8:9] offset:128 nt
	global_load_dwordx4 v[208:211], v144, s[8:9] offset:144 nt
	v_add_u32_e32 v162, 0xa0000, v144
	v_add_u32_e32 v164, 0x30080, v144
	v_mul_f32_e32 v163, v29, v29
	v_mul_f32_e32 v165, v31, v31
	v_fmac_f32_e32 v163, v28, v28
	v_fmac_f32_e32 v165, v30, v30
	v_add_f32_e32 v161, v163, v165
	v_add_f32_e32 v159, v159, v161
	s_waitcnt vmcnt(7)
	v_pk_fma_f32 v[22:23], v[22:23], v[132:133], v[214:215]
	v_pk_fma_f32 v[20:21], v[20:21], v[130:131], v[212:213]
	s_waitcnt vmcnt(6)
; template <int MODE> DI void epilogue(const Epi& E, f32x4 (&acc)[2][2][4][2], const Unit& u, int wr, int wc, int fr, int fq) {
;     ...
;             const f32x4 g0 = *(const f32x4*)(E.gt + bidx * 6144 + col0 + bj * 32), g1 = *(const f32x4*)(E.gt + bidx * 6144 + col0 + bj * 32 + 4);
; #pragma unroll
;             for (int ai = 0; ai < 2; ++ai)
; #pragma unroll
;                 for (int m = 0; m < 4; ++m) {
;                     const unsigned off = E1_OFF(ai, m, bj);
;                     const f32x4 b0 = __builtin_nontemporal_load((const f32x4*)(base + off)), b1 = __builtin_nontemporal_load((const f32x4*)(base + off + 16));
;                     acc[ai][bj][m][0] = b0 + g0 * acc[ai][bj][m][0];
;                     acc[ai][bj][m][1] = b1 + g1 * acc[ai][bj][m][1];
;                     asm volatile("" : "+v"(acc[ai][bj][m][0]), "+v"(acc[ai][bj][m][1]));
;                 }
;             asm volatile("" ::: "memory");
;         }
; #pragma unroll
;         for (int ai = 0; ai < 2; ++ai)
; #pragma unroll
;             for (int m = 0; m < 4; ++m) {
;                 float sq = 0.f;
; #pragma unroll
;                 for (int bj = 0; bj < 2; ++bj)
; #pragma unroll
;                     for (int n = 0; n < 2; ++n) { const f32x4 v = acc[ai][bj][m][n]; sq += (v.x * v.x + v.y * v.y) + (v.z * v.z + v.w * v.w); }
;                 sq += __shfl_xor(sq, 16); sq += __shfl_xor(sq, 32);
;                 if (fq == 0) __hip_atomic_fetch_add(E.rowq + row0 + ai * HALF + m * 16, (1ull << 52) + (unsigned long long)(sq * 65536.0f + 0.5f), __ATOMIC_RELAXED, __HIP_MEMORY_SCOPE_AGENT);
	v_pk_fma_f32 v[2:3], v[2:3], v[180:181], v[218:219]
	v_pk_fma_f32 v[0:1], v[0:1], v[178:179], v[216:217]
	v_add_u32_e32 v175, 0x10080, v144
	global_load_dwordx4 v[212:215], v175, s[8:9] nt
	global_load_dwordx4 v[216:219], v175, s[8:9] offset:16 nt
	v_add_u32_e32 v168, 0xb0000, v144
	v_add_u32_e32 v170, 0x80080, v144
	s_waitcnt vmcnt(7)
	v_pk_fma_f32 v[58:59], v[58:59], v[132:133], v[222:223]
	v_pk_fma_f32 v[56:57], v[56:57], v[130:131], v[220:221]
	s_waitcnt vmcnt(6)
	v_pk_fma_f32 v[38:39], v[38:39], v[180:181], v[226:227]
	v_pk_fma_f32 v[36:37], v[36:37], v[178:179], v[224:225]
	v_add_u32_e32 v173, 0x20080, v144
	global_load_dwordx4 v[220:223], v173, s[8:9] nt
	global_load_dwordx4 v[224:227], v173, s[8:9] offset:16 nt
	s_nop 0
	s_waitcnt vmcnt(7)
	v_pk_fma_f32 v[10:11], v[10:11], v[132:133], v[242:243]
	v_pk_fma_f32 v[8:9], v[8:9], v[130:131], v[240:241]
	s_waitcnt vmcnt(6)
	v_pk_fma_f32 v[14:15], v[14:15], v[180:181], v[246:247]
	v_pk_fma_f32 v[12:13], v[12:13], v[178:179], v[244:245]
	v_add_u32_e32 v175, 0x30080, v144
	global_load_dwordx4 v[240:243], v175, s[8:9] nt
	global_load_dwordx4 v[244:247], v175, s[8:9] offset:16 nt
	s_nop 0
	global_load_dwordx4 v[132:135], v[128:129], off offset:128
	s_nop 0
	global_load_dwordx4 v[128:131], v[128:129], off offset:144
	s_nop 0
	s_waitcnt vmcnt(1)
	v_pk_fma_f32 v[34:35], v[34:35], v[134:135], v[188:189]
	v_pk_fma_f32 v[32:33], v[32:33], v[132:133], v[186:187]
	s_waitcnt vmcnt(0)
	v_pk_fma_f32 v[18:19], v[18:19], v[130:131], v[210:211]
	v_pk_fma_f32 v[16:17], v[16:17], v[128:129], v[208:209]
	v_add_u32_e32 v173, 0x80080, v144
	global_load_dwordx4 v[186:189], v173, s[8:9] nt
	global_load_dwordx4 v[208:211], v173, s[8:9] offset:16 nt
	s_nop 0
	v_mul_f32_e32 v161, v33, v33
	v_mul_f32_e32 v163, v35, v35
	v_mul_f32_e32 v165, v17, v17
	v_mul_f32_e32 v167, v19, v19
	v_fmac_f32_e32 v161, v32, v32
	v_fmac_f32_e32 v163, v34, v34
	v_fmac_f32_e32 v165, v16, v16
	v_fmac_f32_e32 v167, v18, v18
	v_add_f32_e32 v161, v161, v163
	v_add_f32_e32 v163, v165, v167
	v_add_f32_e32 v159, v159, v161
	v_add_f32_e32 v159, v163, v159
	ds_bpermute_b32 v161, v155, v159
	v_xor_b32_e32 v163, 32, v202
	v_cmp_lt_i32_e32 vcc, v163, v157
	s_waitcnt lgkmcnt(0)
	v_add_f32_e32 v159, v159, v161
	v_cndmask_b32_e32 v157, v202, v163, vcc
	v_lshlrev_b32_e32 v157, 2, v157
	ds_bpermute_b32 v161, v157, v159
	v_pk_fma_f32 v[62:63], v[62:63], v[134:135], v[214:215]
	v_pk_fma_f32 v[60:61], v[60:61], v[132:133], v[212:213]
	v_pk_fma_f32 v[42:43], v[42:43], v[130:131], v[218:219]
	v_pk_fma_f32 v[40:41], v[40:41], v[128:129], v[216:217]
	v_add_u32_e32 v175, 0x90080, v144
	global_load_dwordx4 v[212:215], v175, s[8:9] nt
	global_load_dwordx4 v[216:219], v175, s[8:9] offset:16 nt
	s_nop 0
	v_pk_fma_f32 v[26:27], v[26:27], v[134:135], v[222:223]
	v_pk_fma_f32 v[24:25], v[24:25], v[132:133], v[220:221]
	v_pk_fma_f32 v[6:7], v[6:7], v[130:131], v[226:227]
	v_pk_fma_f32 v[4:5], v[4:5], v[128:129], v[224:225]
	v_add_u32_e32 v173, 0xa0080, v144
	global_load_dwordx4 v[220:223], v173, s[8:9] nt
	global_load_dwordx4 v[224:227], v173, s[8:9] offset:16 nt
	s_nop 0
	v_pk_fma_f32 v[66:67], v[66:67], v[134:135], v[242:243]
	v_pk_fma_f32 v[64:65], v[64:65], v[132:133], v[240:241]
	v_pk_fma_f32 v[46:47], v[46:47], v[130:131], v[246:247]
	v_pk_fma_f32 v[44:45], v[44:45], v[128:129], v[244:245]
	v_add_u32_e32 v175, 0xb0080, v144
	global_load_dwordx4 v[240:243], v175, s[8:9] nt
	global_load_dwordx4 v[244:247], v175, s[8:9] offset:16 nt
	s_nop 0
	s_waitcnt vmcnt(7)
	v_pk_fma_f32 v[82:83], v[82:83], v[134:135], v[188:189]
	v_pk_fma_f32 v[80:81], v[80:81], v[132:133], v[186:187]
	s_waitcnt vmcnt(6)
	v_pk_fma_f32 v[74:75], v[74:75], v[130:131], v[210:211]
	v_pk_fma_f32 v[72:73], v[72:73], v[128:129], v[208:209]
	v_add_u32_e32 v178, 0xa0080, v144
	v_add_u32_e32 v180, 0xb0080, v144
	s_waitcnt vmcnt(5)
	v_pk_fma_f32 v[102:103], v[102:103], v[134:135], v[214:215]
	v_pk_fma_f32 v[100:101], v[100:101], v[132:133], v[212:213]
	s_waitcnt vmcnt(4)
	v_pk_fma_f32 v[94:95], v[94:95], v[130:131], v[218:219]
	v_pk_fma_f32 v[92:93], v[92:93], v[128:129], v[216:217]
	s_nop 0
	s_waitcnt vmcnt(3)
	v_pk_fma_f32 v[118:119], v[118:119], v[134:135], v[222:223]
	v_pk_fma_f32 v[116:117], v[116:117], v[132:133], v[220:221]
	s_waitcnt vmcnt(2)
	v_pk_fma_f32 v[110:111], v[110:111], v[130:131], v[226:227]
	v_pk_fma_f32 v[108:109], v[108:109], v[128:129], v[224:225]
	s_nop 0
	s_waitcnt vmcnt(1)
	v_pk_fma_f32 v[126:127], v[126:127], v[134:135], v[242:243]
	v_pk_fma_f32 v[124:125], v[124:125], v[132:133], v[240:241]
	s_waitcnt vmcnt(0)
	v_pk_fma_f32 v[122:123], v[122:123], v[130:131], v[246:247]
	v_pk_fma_f32 v[120:121], v[120:121], v[128:129], v[244:245]
	v_lshl_add_u64 v[128:129], v[184:185], 3, s[10:11]
	s_and_saveexec_b64 s[8:9], s[4:5]
	s_cbranch_execz .LBB0_504
	s_waitcnt lgkmcnt(0)
	v_add_f32_e32 v130, v159, v161
	v_fma_f32 v130, v130, s57, 0.5
	v_trunc_f32_e32 v130, v130
	v_mul_f32_e32 v131, 0x2f800000, v130
	v_floor_f32_e32 v131, v131
	v_fmac_f32_e32 v130, 0xcf800000, v131
	v_cvt_u32_f32_e32 v131, v131
	v_cvt_u32_f32_e32 v130, v130
	v_add_u32_e32 v131, 0x100000, v131
	global_atomic_add_x2 v[128:129], v[130:131], off

; template <int MODE> DI void epilogue(const Epi& E, f32x4 (&acc)[2][2][4][2], const Unit& u, int wr, int wc, int fr, int fq) {
;     ...
;     } else if constexpr (emode == 1) {
;         const int bidx = batch_of_row(u.pm * BM);
;         const char* base = (const char*)((u.pm * BM < TP) ? E.base_p : E.base_s);
;         const int col0 = u.pn * BM + wc * 64 + 8 * fq;
;         const unsigned ro = ((unsigned)row0 * D + (unsigned)col0) * 4u;
;     ...
; #pragma unroll
;         for (int bj = 0; bj < 2; ++bj) {
;             const f32x4 g0 = *(const f32x4*)(E.gt + bidx * 6144 + col0 + bj * 32), g1 = *(const f32x4*)(E.gt + bidx * 6144 + col0 + bj * 32 + 4);
; #pragma unroll
;             for (int ai = 0; ai < 2; ++ai)
; #pragma unroll
;                 for (int m = 0; m < 4; ++m) {
;                     const unsigned off = E1_OFF(ai, m, bj);
;                     const f32x4 b0 = __builtin_nontemporal_load((const f32x4*)(base + off)), b1 = __builtin_nontemporal_load((const f32x4*)(base + off + 16));
;                     acc[ai][bj][m][0] = b0 + g0 * acc[ai][bj][m][0];
;                     acc[ai][bj][m][1] = b1 + g1 * acc[ai][bj][m][1];
;                     asm volatile("" : "+v"(acc[ai][bj][m][0]), "+v"(acc[ai][bj][m][1]));
;                 }
.LBB0_668:
	s_lshl_b32 s8, s17, 8
	v_add_u32_e32 v184, s8, v191
	s_add_i32 s8, s8, 0xffff0000
	s_lshr_b32 s8, s8, 12
	s_lshr_b32 s9, s17, 5
	s_add_i32 s8, s8, 8
	s_cmpk_lt_i32 s17, 0x100
	s_cselect_b32 s8, s9, s8
	s_mulk_i32 s8, 0x1800
	s_ashr_i32 s9, s8, 31
	s_lshl_b64 s[38:39], s[8:9], 2
	v_lshl_or_b32 v180, s16, 8, v196
	s_add_u32 s8, s43, s38
	v_lshlrev_b32_e32 v128, 2, v180
	v_ashrrev_i32_e32 v181, 31, v180
	s_addc_u32 s9, s44, s39
	v_readlane_b32 s60, v254, 38
	v_lshl_add_u32 v144, v184, 12, v128
	v_lshl_add_u64 v[154:155], v[180:181], 2, s[8:9]
	v_readlane_b32 s74, v254, 52
	v_readlane_b32 s75, v254, 53
	global_load_dwordx4 v[128:131], v[154:155], off
	s_nop 3
	global_load_dwordx4 v[202:205], v[154:155], off offset:16
	global_load_dwordx4 v[186:189], v144, s[74:75] nt
	global_load_dwordx4 v[210:213], v144, s[74:75] offset:16 nt
	v_add_u32_e32 v175, 0x10000, v144
	global_load_dwordx4 v[214:217], v175, s[74:75] nt
	global_load_dwordx4 v[218:221], v175, s[74:75] offset:16 nt
	v_add_u32_e32 v173, 0x20000, v144
	global_load_dwordx4 v[222:225], v173, s[74:75] nt
	global_load_dwordx4 v[226:229], v173, s[74:75] offset:16 nt
	v_add_u32_e32 v175, 0x30000, v144
	global_load_dwordx4 v[240:243], v175, s[74:75] nt
	global_load_dwordx4 v[244:247], v175, s[74:75] offset:16 nt
	v_add_u32_e32 v166, 0x10000, v144
	v_add_u32_e32 v172, 0x20000, v144
	v_add_u32_e32 v176, 0x30000, v144
	v_add_u32_e32 v174, 0x90080, v144
	v_add_u32_e32 v178, 0xa0080, v144
	v_add_u32_e32 v182, 0xb0080, v144
	v_ashrrev_i32_e32 v185, 31, v184
	v_readlane_b32 s61, v254, 39
	v_readlane_b32 s62, v254, 40
	v_readlane_b32 s63, v254, 41
	v_readlane_b32 s64, v254, 42
	v_readlane_b32 s65, v254, 43
	v_readlane_b32 s66, v254, 44
	v_readlane_b32 s67, v254, 45
	v_readlane_b32 s68, v254, 46
	v_readlane_b32 s69, v254, 47
	v_readlane_b32 s70, v254, 48
	v_readlane_b32 s71, v254, 49
	v_readlane_b32 s72, v254, 50
	v_readlane_b32 s73, v254, 51
	s_waitcnt vmcnt(7)
	v_pk_fma_f32 v[50:51], v[50:51], v[130:131], v[188:189]
	v_pk_fma_f32 v[48:49], v[48:49], v[128:129], v[186:187]
	s_waitcnt vmcnt(6)
	v_pk_fma_f32 v[30:31], v[30:31], v[204:205], v[212:213]
	v_pk_fma_f32 v[28:29], v[28:29], v[202:203], v[210:211]
	v_add_u32_e32 v173, 0x80000, v144
	global_load_dwordx4 v[186:189], v173, s[74:75] nt
	global_load_dwordx4 v[210:213], v173, s[74:75] offset:16 nt
	s_nop 0
	s_waitcnt vmcnt(7)
	v_pk_fma_f32 v[70:71], v[70:71], v[130:131], v[216:217]
	v_pk_fma_f32 v[68:69], v[68:69], v[128:129], v[214:215]
	s_waitcnt vmcnt(6)
	v_pk_fma_f32 v[54:55], v[54:55], v[204:205], v[220:221]
	v_pk_fma_f32 v[52:53], v[52:53], v[202:203], v[218:219]
	v_add_u32_e32 v175, 0x90000, v144
	global_load_dwordx4 v[214:217], v175, s[74:75] nt
	global_load_dwordx4 v[218:221], v175, s[74:75] offset:16 nt
	s_nop 0
	s_waitcnt vmcnt(7)
	v_pk_fma_f32 v[86:87], v[86:87], v[130:131], v[224:225]
	v_pk_fma_f32 v[84:85], v[84:85], v[128:129], v[222:223]
	s_waitcnt vmcnt(6)
	v_pk_fma_f32 v[78:79], v[78:79], v[204:205], v[228:229]
	v_pk_fma_f32 v[76:77], v[76:77], v[202:203], v[226:227]
	v_add_u32_e32 v173, 0xa0000, v144
	global_load_dwordx4 v[222:225], v173, s[74:75] nt
	global_load_dwordx4 v[226:229], v173, s[74:75] offset:16 nt
	v_add_u32_e32 v156, 0x80000, v144
	v_and_b32_e32 v157, 64, v200
	v_add_u32_e32 v157, 64, v157
	s_waitcnt vmcnt(7)
	v_pk_fma_f32 v[98:99], v[98:99], v[130:131], v[242:243]
	v_pk_fma_f32 v[96:97], v[96:97], v[128:129], v[240:241]
	s_waitcnt vmcnt(6)
	v_pk_fma_f32 v[90:91], v[90:91], v[204:205], v[246:247]
	v_pk_fma_f32 v[88:89], v[88:89], v[202:203], v[244:245]
	v_add_u32_e32 v175, 0xb0000, v144
	global_load_dwordx4 v[240:243], v175, s[74:75] nt
	global_load_dwordx4 v[244:247], v175, s[74:75] offset:16 nt
	v_add_u32_e32 v160, 0x90000, v144
	v_add_u32_e32 v158, 0x20080, v144
	v_mul_f32_e32 v159, v49, v49
	v_mul_f32_e32 v161, v51, v51
	v_fmac_f32_e32 v159, v48, v48
	v_fmac_f32_e32 v161, v50, v50
	v_add_f32_e32 v159, v159, v161
	s_waitcnt vmcnt(7)
	v_pk_fma_f32 v[114:115], v[114:115], v[130:131], v[188:189]
	v_pk_fma_f32 v[112:113], v[112:113], v[128:129], v[186:187]
	s_waitcnt vmcnt(6)
	v_pk_fma_f32 v[106:107], v[106:107], v[204:205], v[212:213]
	v_pk_fma_f32 v[104:105], v[104:105], v[202:203], v[210:211]
	global_load_dwordx4 v[186:189], v144, s[74:75] offset:128 nt
	global_load_dwordx4 v[210:213], v144, s[74:75] offset:144 nt
	v_add_u32_e32 v162, 0xa0000, v144
	v_add_u32_e32 v164, 0x30080, v144
	v_mul_f32_e32 v163, v29, v29
	v_mul_f32_e32 v165, v31, v31
	v_fmac_f32_e32 v163, v28, v28
	v_fmac_f32_e32 v165, v30, v30
	v_add_f32_e32 v161, v163, v165
	v_add_f32_e32 v159, v159, v161
	s_waitcnt vmcnt(7)
	v_pk_fma_f32 v[22:23], v[22:23], v[130:131], v[216:217]
	v_pk_fma_f32 v[20:21], v[20:21], v[128:129], v[214:215]
	s_waitcnt vmcnt(6)
	v_pk_fma_f32 v[2:3], v[2:3], v[204:205], v[220:221]
	v_pk_fma_f32 v[0:1], v[0:1], v[202:203], v[218:219]
	v_add_u32_e32 v175, 0x10080, v144
	global_load_dwordx4 v[214:217], v175, s[74:75] nt
	global_load_dwordx4 v[218:221], v175, s[74:75] offset:16 nt
	v_add_u32_e32 v168, 0xb0000, v144
	v_add_u32_e32 v170, 0x80080, v144
	s_waitcnt vmcnt(7)
; template <int MODE> DI void epilogue(const Epi& E, f32x4 (&acc)[2][2][4][2], const Unit& u, int wr, int wc, int fr, int fq) {
;     ...
;             const f32x4 g0 = *(const f32x4*)(E.gt + bidx * 6144 + col0 + bj * 32), g1 = *(const f32x4*)(E.gt + bidx * 6144 + col0 + bj * 32 + 4);
; #pragma unroll
;             for (int ai = 0; ai < 2; ++ai)
; #pragma unroll
;                 for (int m = 0; m < 4; ++m) {
;                     const unsigned off = E1_OFF(ai, m, bj);
;                     const f32x4 b0 = __builtin_nontemporal_load((const f32x4*)(base + off)), b1 = __builtin_nontemporal_load((const f32x4*)(base + off + 16));
;                     acc[ai][bj][m][0] = b0 + g0 * acc[ai][bj][m][0];
;                     acc[ai][bj][m][1] = b1 + g1 * acc[ai][bj][m][1];
;                     asm volatile("" : "+v"(acc[ai][bj][m][0]), "+v"(acc[ai][bj][m][1]));
;                 }
;             asm volatile("" ::: "memory");
;         }
; #pragma unroll
;         for (int ai = 0; ai < 2; ++ai)
; #pragma unroll
;             for (int m = 0; m < 4; ++m) {
;                 float sq = 0.f;
; #pragma unroll
;                 for (int bj = 0; bj < 2; ++bj)
; #pragma unroll
;                     for (int n = 0; n < 2; ++n) { const f32x4 v = acc[ai][bj][m][n]; sq += (v.x * v.x + v.y * v.y) + (v.z * v.z + v.w * v.w); }
;                 sq += __shfl_xor(sq, 16); sq += __shfl_xor(sq, 32);
;                 if (fq == 0) __hip_atomic_fetch_add(E.rowq + row0 + ai * HALF + m * 16, (1ull << 52) + (unsigned long long)(sq * 65536.0f + 0.5f), __ATOMIC_RELAXED, __HIP_MEMORY_SCOPE_AGENT);
	v_pk_fma_f32 v[58:59], v[58:59], v[130:131], v[224:225]
	v_pk_fma_f32 v[56:57], v[56:57], v[128:129], v[222:223]
	s_waitcnt vmcnt(6)
	v_pk_fma_f32 v[38:39], v[38:39], v[204:205], v[228:229]
	v_pk_fma_f32 v[36:37], v[36:37], v[202:203], v[226:227]
	v_add_u32_e32 v173, 0x20080, v144
	global_load_dwordx4 v[222:225], v173, s[74:75] nt
	global_load_dwordx4 v[226:229], v173, s[74:75] offset:16 nt
	s_nop 0
	s_waitcnt vmcnt(7)
	v_pk_fma_f32 v[10:11], v[10:11], v[130:131], v[242:243]
	v_pk_fma_f32 v[8:9], v[8:9], v[128:129], v[240:241]
	s_waitcnt vmcnt(6)
	v_pk_fma_f32 v[14:15], v[14:15], v[204:205], v[246:247]
	v_pk_fma_f32 v[12:13], v[12:13], v[202:203], v[244:245]
	v_add_u32_e32 v175, 0x30080, v144
	global_load_dwordx4 v[240:243], v175, s[74:75] nt
	global_load_dwordx4 v[244:247], v175, s[74:75] offset:16 nt
	s_nop 0
	global_load_dwordx4 v[132:135], v[154:155], off offset:128
	global_load_dwordx4 v[128:131], v[154:155], off offset:144
	v_add_u32_e32 v154, 0x10080, v144
	v_xor_b32_e32 v155, 16, v200
	v_cmp_lt_i32_e32 vcc, v155, v157
	s_waitcnt vmcnt(1)
	v_pk_fma_f32 v[34:35], v[34:35], v[134:135], v[188:189]
	v_pk_fma_f32 v[32:33], v[32:33], v[132:133], v[186:187]
	s_waitcnt vmcnt(0)
	v_pk_fma_f32 v[18:19], v[18:19], v[130:131], v[212:213]
	v_pk_fma_f32 v[16:17], v[16:17], v[128:129], v[210:211]
	v_add_u32_e32 v173, 0x80080, v144
	global_load_dwordx4 v[186:189], v173, s[74:75] nt
	global_load_dwordx4 v[210:213], v173, s[74:75] offset:16 nt
	v_cndmask_b32_e32 v155, v200, v155, vcc
	v_mul_f32_e32 v161, v33, v33
	v_mul_f32_e32 v163, v35, v35
	v_mul_f32_e32 v165, v17, v17
	v_mul_f32_e32 v167, v19, v19
	v_fmac_f32_e32 v161, v32, v32
	v_fmac_f32_e32 v163, v34, v34
	v_fmac_f32_e32 v165, v16, v16
	v_fmac_f32_e32 v167, v18, v18
	v_add_f32_e32 v161, v161, v163
	v_add_f32_e32 v163, v165, v167
	v_add_f32_e32 v159, v159, v161
	v_lshlrev_b32_e32 v155, 2, v155
	v_add_f32_e32 v159, v163, v159
	ds_bpermute_b32 v161, v155, v159
	v_xor_b32_e32 v163, 32, v200
	v_cmp_lt_i32_e32 vcc, v163, v157
	s_waitcnt lgkmcnt(0)
	v_add_f32_e32 v159, v159, v161
	v_cndmask_b32_e32 v157, v200, v163, vcc
	v_lshlrev_b32_e32 v157, 2, v157
	ds_bpermute_b32 v161, v157, v159
	v_pk_fma_f32 v[62:63], v[62:63], v[134:135], v[216:217]
	v_pk_fma_f32 v[60:61], v[60:61], v[132:133], v[214:215]
	v_pk_fma_f32 v[42:43], v[42:43], v[130:131], v[220:221]
	v_pk_fma_f32 v[40:41], v[40:41], v[128:129], v[218:219]
	v_add_u32_e32 v175, 0x90080, v144
	global_load_dwordx4 v[214:217], v175, s[74:75] nt
	global_load_dwordx4 v[218:221], v175, s[74:75] offset:16 nt
	s_nop 0
	v_pk_fma_f32 v[26:27], v[26:27], v[134:135], v[224:225]
	v_pk_fma_f32 v[24:25], v[24:25], v[132:133], v[222:223]
	v_pk_fma_f32 v[6:7], v[6:7], v[130:131], v[228:229]
	v_pk_fma_f32 v[4:5], v[4:5], v[128:129], v[226:227]
	v_add_u32_e32 v173, 0xa0080, v144
	global_load_dwordx4 v[222:225], v173, s[74:75] nt
	global_load_dwordx4 v[226:229], v173, s[74:75] offset:16 nt
	s_nop 0
	v_pk_fma_f32 v[66:67], v[66:67], v[134:135], v[242:243]
	v_pk_fma_f32 v[64:65], v[64:65], v[132:133], v[240:241]
	v_pk_fma_f32 v[46:47], v[46:47], v[130:131], v[246:247]
	v_pk_fma_f32 v[44:45], v[44:45], v[128:129], v[244:245]
	v_add_u32_e32 v175, 0xb0080, v144
	global_load_dwordx4 v[240:243], v175, s[74:75] nt
	global_load_dwordx4 v[244:247], v175, s[74:75] offset:16 nt
	s_nop 0
	s_waitcnt vmcnt(7)
	v_pk_fma_f32 v[82:83], v[82:83], v[134:135], v[188:189]
	v_pk_fma_f32 v[80:81], v[80:81], v[132:133], v[186:187]
	s_waitcnt vmcnt(6)
	v_pk_fma_f32 v[74:75], v[74:75], v[130:131], v[212:213]
	v_pk_fma_f32 v[72:73], v[72:73], v[128:129], v[210:211]
	s_nop 0
	s_waitcnt vmcnt(5)
	v_pk_fma_f32 v[102:103], v[102:103], v[134:135], v[216:217]
	v_pk_fma_f32 v[100:101], v[100:101], v[132:133], v[214:215]
	s_waitcnt vmcnt(4)
	v_pk_fma_f32 v[94:95], v[94:95], v[130:131], v[220:221]
	v_pk_fma_f32 v[92:93], v[92:93], v[128:129], v[218:219]
	s_nop 0
	s_waitcnt vmcnt(3)
	v_pk_fma_f32 v[118:119], v[118:119], v[134:135], v[224:225]
	v_pk_fma_f32 v[116:117], v[116:117], v[132:133], v[222:223]
	s_waitcnt vmcnt(2)
	v_pk_fma_f32 v[110:111], v[110:111], v[130:131], v[228:229]
	v_pk_fma_f32 v[108:109], v[108:109], v[128:129], v[226:227]
	s_nop 0
	s_waitcnt vmcnt(1)
	v_pk_fma_f32 v[126:127], v[126:127], v[134:135], v[242:243]
	v_pk_fma_f32 v[124:125], v[124:125], v[132:133], v[240:241]
	s_waitcnt vmcnt(0)
	v_pk_fma_f32 v[122:123], v[122:123], v[130:131], v[246:247]
	v_pk_fma_f32 v[120:121], v[120:121], v[128:129], v[244:245]
	v_lshl_add_u64 v[128:129], v[184:185], 3, s[2:3]
	s_and_saveexec_b64 s[8:9], s[4:5]
	s_cbranch_execz .LBB0_670
	s_waitcnt lgkmcnt(0)
	v_add_f32_e32 v130, v159, v161
	v_fma_f32 v130, v130, s54, 0.5
	v_trunc_f32_e32 v130, v130
	v_mul_f32_e32 v131, 0x2f800000, v130
	v_floor_f32_e32 v131, v131
	v_fmac_f32_e32 v130, 0xcf800000, v131
	v_cvt_u32_f32_e32 v131, v131
	v_cvt_u32_f32_e32 v130, v130
	v_add_u32_e32 v131, 0x100000, v131
	global_atomic_add_x2 v[128:129], v[130:131], off

; template <int MODE> DI void epilogue(const Epi& E, f32x4 (&acc)[2][2][4][2], const Unit& u, int wr, int wc, int fr, int fq) {
;     ...
;     } else if constexpr (emode == 1) {
;         const int bidx = batch_of_row(u.pm * BM);
;         const char* base = (const char*)((u.pm * BM < TP) ? E.base_p : E.base_s);
;         const int col0 = u.pn * BM + wc * 64 + 8 * fq;
;         const unsigned ro = ((unsigned)row0 * D + (unsigned)col0) * 4u;
;     ...
; #pragma unroll
;         for (int bj = 0; bj < 2; ++bj) {
;             const f32x4 g0 = *(const f32x4*)(E.gt + bidx * 6144 + col0 + bj * 32), g1 = *(const f32x4*)(E.gt + bidx * 6144 + col0 + bj * 32 + 4);
; #pragma unroll
;             for (int ai = 0; ai < 2; ++ai)
; #pragma unroll
;                 for (int m = 0; m < 4; ++m) {
;                     const unsigned off = E1_OFF(ai, m, bj);
;                     const f32x4 b0 = __builtin_nontemporal_load((const f32x4*)(base + off)), b1 = __builtin_nontemporal_load((const f32x4*)(base + off + 16));
;                     acc[ai][bj][m][0] = b0 + g0 * acc[ai][bj][m][0];
;                     acc[ai][bj][m][1] = b1 + g1 * acc[ai][bj][m][1];
;                     asm volatile("" : "+v"(acc[ai][bj][m][0]), "+v"(acc[ai][bj][m][1]));
;                 }
.LBB0_999:
	s_lshl_b32 s9, s10, 8
	v_add_u32_e32 v184, s9, v191
	s_add_i32 s9, s9, 0xffff0000
	s_lshr_b32 s9, s9, 12
	s_lshr_b32 s11, s10, 5
	s_add_i32 s9, s9, 8
	s_cmpk_lt_i32 s10, 0x100
	s_cselect_b32 s9, s11, s9
	v_lshl_or_b32 v180, s8, 8, v196
	s_mul_i32 s8, s9, 0x1800
	s_ashr_i32 s9, s8, 31
	s_lshl_b64 s[42:43], s[8:9], 2
	s_add_u32 s8, s47, s42
	v_lshlrev_b32_e32 v128, 2, v180
	v_ashrrev_i32_e32 v181, 31, v180
	s_addc_u32 s9, s48, s43
	v_readlane_b32 s72, v254, 38
	v_lshl_add_u32 v144, v184, 12, v128
	v_lshl_add_u64 v[154:155], v[180:181], 2, s[8:9]
	v_readlane_b32 s86, v254, 52
	v_readlane_b32 s87, v254, 53
	global_load_dwordx4 v[128:131], v[154:155], off
	s_nop 3
	global_load_dwordx4 v[176:179], v[154:155], off offset:16
	global_load_dwordx4 v[186:189], v144, s[86:87] nt
	global_load_dwordx4 v[210:213], v144, s[86:87] offset:16 nt
	v_add_u32_e32 v171, 0x10000, v144
	global_load_dwordx4 v[214:217], v171, s[86:87] nt
	global_load_dwordx4 v[218:221], v171, s[86:87] offset:16 nt
	v_add_u32_e32 v169, 0x20000, v144
	global_load_dwordx4 v[222:225], v169, s[86:87] nt
	global_load_dwordx4 v[226:229], v169, s[86:87] offset:16 nt
	v_add_u32_e32 v171, 0x30000, v144
	global_load_dwordx4 v[240:243], v171, s[86:87] nt
	global_load_dwordx4 v[244:247], v171, s[86:87] offset:16 nt
	v_add_u32_e32 v166, 0x10000, v144
	v_add_u32_e32 v170, 0x20000, v144
	v_add_u32_e32 v174, 0x30000, v144
	v_add_u32_e32 v168, 0xb0000, v144
	v_add_u32_e32 v172, 0x80080, v144
	v_add_u32_e32 v182, 0xb0080, v144
	v_ashrrev_i32_e32 v185, 31, v184
	v_readlane_b32 s73, v254, 39
	v_readlane_b32 s74, v254, 40
	v_readlane_b32 s75, v254, 41
	v_readlane_b32 s76, v254, 42
	v_readlane_b32 s77, v254, 43
	v_readlane_b32 s78, v254, 44
	v_readlane_b32 s79, v254, 45
	v_readlane_b32 s80, v254, 46
	v_readlane_b32 s81, v254, 47
	v_readlane_b32 s82, v254, 48
	v_readlane_b32 s83, v254, 49
	v_readlane_b32 s84, v254, 50
	v_readlane_b32 s85, v254, 51
	s_waitcnt vmcnt(7)
	v_pk_fma_f32 v[38:39], v[38:39], v[130:131], v[188:189]
	v_pk_fma_f32 v[36:37], v[36:37], v[128:129], v[186:187]
	s_waitcnt vmcnt(6)
	v_pk_fma_f32 v[22:23], v[22:23], v[178:179], v[212:213]
	v_pk_fma_f32 v[20:21], v[20:21], v[176:177], v[210:211]
	v_add_u32_e32 v169, 0x80000, v144
	global_load_dwordx4 v[186:189], v169, s[86:87] nt
	global_load_dwordx4 v[210:213], v169, s[86:87] offset:16 nt
	s_nop 0
	s_waitcnt vmcnt(7)
	v_pk_fma_f32 v[62:63], v[62:63], v[130:131], v[216:217]
	v_pk_fma_f32 v[60:61], v[60:61], v[128:129], v[214:215]
	s_waitcnt vmcnt(6)
	v_pk_fma_f32 v[46:47], v[46:47], v[178:179], v[220:221]
	v_pk_fma_f32 v[44:45], v[44:45], v[176:177], v[218:219]
	v_add_u32_e32 v171, 0x90000, v144
	global_load_dwordx4 v[214:217], v171, s[86:87] nt
	global_load_dwordx4 v[218:221], v171, s[86:87] offset:16 nt
	s_nop 0
	s_waitcnt vmcnt(7)
	v_pk_fma_f32 v[82:83], v[82:83], v[130:131], v[224:225]
	v_pk_fma_f32 v[80:81], v[80:81], v[128:129], v[222:223]
	s_waitcnt vmcnt(6)
	v_pk_fma_f32 v[74:75], v[74:75], v[178:179], v[228:229]
	v_pk_fma_f32 v[72:73], v[72:73], v[176:177], v[226:227]
	v_add_u32_e32 v169, 0xa0000, v144
	global_load_dwordx4 v[222:225], v169, s[86:87] nt
	global_load_dwordx4 v[226:229], v169, s[86:87] offset:16 nt
	v_add_u32_e32 v156, 0x80000, v144
	v_and_b32_e32 v157, 64, v200
	v_add_u32_e32 v157, 64, v157
	s_waitcnt vmcnt(7)
	v_pk_fma_f32 v[98:99], v[98:99], v[130:131], v[242:243]
	v_pk_fma_f32 v[96:97], v[96:97], v[128:129], v[240:241]
	s_waitcnt vmcnt(6)
	v_pk_fma_f32 v[90:91], v[90:91], v[178:179], v[246:247]
	v_pk_fma_f32 v[88:89], v[88:89], v[176:177], v[244:245]
	v_add_u32_e32 v171, 0xb0000, v144
	global_load_dwordx4 v[240:243], v171, s[86:87] nt
	global_load_dwordx4 v[244:247], v171, s[86:87] offset:16 nt
	v_add_u32_e32 v160, 0x90000, v144
	v_add_u32_e32 v158, 0x20080, v144
	v_mul_f32_e32 v159, v37, v37
	v_mul_f32_e32 v161, v39, v39
	v_fmac_f32_e32 v159, v36, v36
	v_fmac_f32_e32 v161, v38, v38
	v_add_f32_e32 v159, v159, v161
	s_waitcnt vmcnt(7)
	v_pk_fma_f32 v[114:115], v[114:115], v[130:131], v[188:189]
	v_pk_fma_f32 v[112:113], v[112:113], v[128:129], v[186:187]
	s_waitcnt vmcnt(6)
	v_pk_fma_f32 v[106:107], v[106:107], v[178:179], v[212:213]
	v_pk_fma_f32 v[104:105], v[104:105], v[176:177], v[210:211]
	global_load_dwordx4 v[186:189], v144, s[86:87] offset:128 nt
	global_load_dwordx4 v[210:213], v144, s[86:87] offset:144 nt
	v_add_u32_e32 v162, 0xa0000, v144
	v_add_u32_e32 v164, 0x30080, v144
	v_mul_f32_e32 v163, v21, v21
	v_mul_f32_e32 v165, v23, v23
	v_fmac_f32_e32 v163, v20, v20
	v_fmac_f32_e32 v165, v22, v22
	v_add_f32_e32 v161, v163, v165
	v_add_f32_e32 v159, v159, v161
	s_waitcnt vmcnt(7)
	v_pk_fma_f32 v[26:27], v[26:27], v[130:131], v[216:217]
	v_pk_fma_f32 v[24:25], v[24:25], v[128:129], v[214:215]
	s_waitcnt vmcnt(6)
	v_pk_fma_f32 v[2:3], v[2:3], v[178:179], v[220:221]
	v_pk_fma_f32 v[0:1], v[0:1], v[176:177], v[218:219]
	v_add_u32_e32 v171, 0x10080, v144
	global_load_dwordx4 v[214:217], v171, s[86:87] nt
	global_load_dwordx4 v[218:221], v171, s[86:87] offset:16 nt
	s_nop 0
	s_waitcnt vmcnt(7)
; template <int MODE> DI void epilogue(const Epi& E, f32x4 (&acc)[2][2][4][2], const Unit& u, int wr, int wc, int fr, int fq) {
;     ...
;             const f32x4 g0 = *(const f32x4*)(E.gt + bidx * 6144 + col0 + bj * 32), g1 = *(const f32x4*)(E.gt + bidx * 6144 + col0 + bj * 32 + 4);
; #pragma unroll
;             for (int ai = 0; ai < 2; ++ai)
; #pragma unroll
;                 for (int m = 0; m < 4; ++m) {
;                     const unsigned off = E1_OFF(ai, m, bj);
;                     const f32x4 b0 = __builtin_nontemporal_load((const f32x4*)(base + off)), b1 = __builtin_nontemporal_load((const f32x4*)(base + off + 16));
;                     acc[ai][bj][m][0] = b0 + g0 * acc[ai][bj][m][0];
;                     acc[ai][bj][m][1] = b1 + g1 * acc[ai][bj][m][1];
;                     asm volatile("" : "+v"(acc[ai][bj][m][0]), "+v"(acc[ai][bj][m][1]));
;                 }
;             asm volatile("" ::: "memory");
;         }
; #pragma unroll
;         for (int ai = 0; ai < 2; ++ai)
; #pragma unroll
;             for (int m = 0; m < 4; ++m) {
;                 float sq = 0.f;
; #pragma unroll
;                 for (int bj = 0; bj < 2; ++bj)
; #pragma unroll
;                     for (int n = 0; n < 2; ++n) { const f32x4 v = acc[ai][bj][m][n]; sq += (v.x * v.x + v.y * v.y) + (v.z * v.z + v.w * v.w); }
;                 sq += __shfl_xor(sq, 16); sq += __shfl_xor(sq, 32);
;                 if (fq == 0) __hip_atomic_fetch_add(E.rowq + row0 + ai * HALF + m * 16, (1ull << 52) + (unsigned long long)(sq * 65536.0f + 0.5f), __ATOMIC_RELAXED, __HIP_MEMORY_SCOPE_AGENT);
	v_pk_fma_f32 v[58:59], v[58:59], v[130:131], v[224:225]
	v_pk_fma_f32 v[56:57], v[56:57], v[128:129], v[222:223]
	s_waitcnt vmcnt(6)
	v_pk_fma_f32 v[42:43], v[42:43], v[178:179], v[228:229]
	v_pk_fma_f32 v[40:41], v[40:41], v[176:177], v[226:227]
	v_add_u32_e32 v169, 0x20080, v144
	global_load_dwordx4 v[222:225], v169, s[86:87] nt
	global_load_dwordx4 v[226:229], v169, s[86:87] offset:16 nt
	s_nop 0
	s_waitcnt vmcnt(7)
	v_pk_fma_f32 v[10:11], v[10:11], v[130:131], v[242:243]
	v_pk_fma_f32 v[8:9], v[8:9], v[128:129], v[240:241]
	s_waitcnt vmcnt(6)
	v_pk_fma_f32 v[14:15], v[14:15], v[178:179], v[246:247]
	v_pk_fma_f32 v[12:13], v[12:13], v[176:177], v[244:245]
	v_add_u32_e32 v171, 0x30080, v144
	global_load_dwordx4 v[240:243], v171, s[86:87] nt
	global_load_dwordx4 v[244:247], v171, s[86:87] offset:16 nt
	s_nop 0
	global_load_dwordx4 v[132:135], v[154:155], off offset:128
	global_load_dwordx4 v[128:131], v[154:155], off offset:144
	v_add_u32_e32 v154, 0x10080, v144
	v_xor_b32_e32 v155, 16, v200
	v_cmp_lt_i32_e32 vcc, v155, v157
	s_waitcnt vmcnt(1)
	v_pk_fma_f32 v[34:35], v[34:35], v[134:135], v[188:189]
	v_pk_fma_f32 v[32:33], v[32:33], v[132:133], v[186:187]
	s_waitcnt vmcnt(0)
	v_pk_fma_f32 v[18:19], v[18:19], v[130:131], v[212:213]
	v_pk_fma_f32 v[16:17], v[16:17], v[128:129], v[210:211]
	v_add_u32_e32 v169, 0x80080, v144
	global_load_dwordx4 v[186:189], v169, s[86:87] nt
	global_load_dwordx4 v[210:213], v169, s[86:87] offset:16 nt
	v_cndmask_b32_e32 v155, v200, v155, vcc
	v_mul_f32_e32 v161, v33, v33
	v_mul_f32_e32 v163, v35, v35
	v_mul_f32_e32 v165, v17, v17
	v_mul_f32_e32 v167, v19, v19
	v_fmac_f32_e32 v161, v32, v32
	v_fmac_f32_e32 v163, v34, v34
	v_fmac_f32_e32 v165, v16, v16
	v_fmac_f32_e32 v167, v18, v18
	v_add_f32_e32 v161, v161, v163
	v_add_f32_e32 v163, v165, v167
	v_add_f32_e32 v159, v159, v161
	v_lshlrev_b32_e32 v155, 2, v155
	v_add_f32_e32 v159, v163, v159
	ds_bpermute_b32 v161, v155, v159
	v_xor_b32_e32 v163, 32, v200
	v_cmp_lt_i32_e32 vcc, v163, v157
	s_waitcnt lgkmcnt(0)
	v_add_f32_e32 v159, v159, v161
	v_cndmask_b32_e32 v157, v200, v163, vcc
	v_lshlrev_b32_e32 v157, 2, v157
	ds_bpermute_b32 v161, v157, v159
	v_pk_fma_f32 v[66:67], v[66:67], v[134:135], v[216:217]
	v_pk_fma_f32 v[64:65], v[64:65], v[132:133], v[214:215]
	v_pk_fma_f32 v[50:51], v[50:51], v[130:131], v[220:221]
	v_pk_fma_f32 v[48:49], v[48:49], v[128:129], v[218:219]
	v_add_u32_e32 v171, 0x90080, v144
	global_load_dwordx4 v[214:217], v171, s[86:87] nt
	global_load_dwordx4 v[218:221], v171, s[86:87] offset:16 nt
	s_nop 0
	v_pk_fma_f32 v[30:31], v[30:31], v[134:135], v[224:225]
	v_pk_fma_f32 v[28:29], v[28:29], v[132:133], v[222:223]
	v_pk_fma_f32 v[6:7], v[6:7], v[130:131], v[228:229]
	v_pk_fma_f32 v[4:5], v[4:5], v[128:129], v[226:227]
	v_add_u32_e32 v169, 0xa0080, v144
	global_load_dwordx4 v[222:225], v169, s[86:87] nt
	global_load_dwordx4 v[226:229], v169, s[86:87] offset:16 nt
	s_nop 0
	v_pk_fma_f32 v[70:71], v[70:71], v[134:135], v[242:243]
	v_pk_fma_f32 v[68:69], v[68:69], v[132:133], v[240:241]
	v_pk_fma_f32 v[54:55], v[54:55], v[130:131], v[246:247]
	v_pk_fma_f32 v[52:53], v[52:53], v[128:129], v[244:245]
	v_add_u32_e32 v171, 0xb0080, v144
	global_load_dwordx4 v[240:243], v171, s[86:87] nt
	global_load_dwordx4 v[244:247], v171, s[86:87] offset:16 nt
	v_add_u32_e32 v176, 0x90080, v144
	v_add_u32_e32 v178, 0xa0080, v144
	s_waitcnt vmcnt(7)
	v_pk_fma_f32 v[86:87], v[86:87], v[134:135], v[188:189]
	v_pk_fma_f32 v[84:85], v[84:85], v[132:133], v[186:187]
	s_waitcnt vmcnt(6)
	v_pk_fma_f32 v[78:79], v[78:79], v[130:131], v[212:213]
	v_pk_fma_f32 v[76:77], v[76:77], v[128:129], v[210:211]
	s_nop 0
	s_waitcnt vmcnt(5)
	v_pk_fma_f32 v[102:103], v[102:103], v[134:135], v[216:217]
	v_pk_fma_f32 v[100:101], v[100:101], v[132:133], v[214:215]
	s_waitcnt vmcnt(4)
	v_pk_fma_f32 v[94:95], v[94:95], v[130:131], v[220:221]
	v_pk_fma_f32 v[92:93], v[92:93], v[128:129], v[218:219]
	s_nop 0
	s_waitcnt vmcnt(3)
	v_pk_fma_f32 v[118:119], v[118:119], v[134:135], v[224:225]
	v_pk_fma_f32 v[116:117], v[116:117], v[132:133], v[222:223]
	s_waitcnt vmcnt(2)
	v_pk_fma_f32 v[110:111], v[110:111], v[130:131], v[228:229]
	v_pk_fma_f32 v[108:109], v[108:109], v[128:129], v[226:227]
	s_nop 0
	s_waitcnt vmcnt(1)
	v_pk_fma_f32 v[126:127], v[126:127], v[134:135], v[242:243]
	v_pk_fma_f32 v[124:125], v[124:125], v[132:133], v[240:241]
	s_waitcnt vmcnt(0)
	v_pk_fma_f32 v[122:123], v[122:123], v[130:131], v[246:247]
	v_pk_fma_f32 v[120:121], v[120:121], v[128:129], v[244:245]
	v_lshl_add_u64 v[128:129], v[184:185], 3, s[2:3]
	s_and_saveexec_b64 s[8:9], s[4:5]
	s_cbranch_execz .LBB0_1001
	s_waitcnt lgkmcnt(0)
	v_add_f32_e32 v130, v159, v161
	v_fma_f32 v130, v130, s58, 0.5
	v_trunc_f32_e32 v130, v130
	v_mul_f32_e32 v131, 0x2f800000, v130
	v_floor_f32_e32 v131, v131
	v_fmac_f32_e32 v130, 0xcf800000, v131
	v_cvt_u32_f32_e32 v131, v131
	v_cvt_u32_f32_e32 v130, v130
	v_add_u32_e32 v131, 0x100000, v131
	global_atomic_add_x2 v[128:129], v[130:131], off

; template <int MODE> DI void epilogue(const Epi& E, f32x4 (&acc)[2][2][4][2], const Unit& u, int wr, int wc, int fr, int fq) {
;     ...
;     } else if constexpr (emode == 1) {
;         const int bidx = batch_of_row(u.pm * BM);
;         const char* base = (const char*)((u.pm * BM < TP) ? E.base_p : E.base_s);
;         const int col0 = u.pn * BM + wc * 64 + 8 * fq;
;         const unsigned ro = ((unsigned)row0 * D + (unsigned)col0) * 4u;
;     ...
; #pragma unroll
;         for (int bj = 0; bj < 2; ++bj) {
;             const f32x4 g0 = *(const f32x4*)(E.gt + bidx * 6144 + col0 + bj * 32), g1 = *(const f32x4*)(E.gt + bidx * 6144 + col0 + bj * 32 + 4);
; #pragma unroll
;             for (int ai = 0; ai < 2; ++ai)
; #pragma unroll
;                 for (int m = 0; m < 4; ++m) {
;                     const unsigned off = E1_OFF(ai, m, bj);
;                     const f32x4 b0 = __builtin_nontemporal_load((const f32x4*)(base + off)), b1 = __builtin_nontemporal_load((const f32x4*)(base + off + 16));
;                     acc[ai][bj][m][0] = b0 + g0 * acc[ai][bj][m][0];
;                     acc[ai][bj][m][1] = b1 + g1 * acc[ai][bj][m][1];
;                     asm volatile("" : "+v"(acc[ai][bj][m][0]), "+v"(acc[ai][bj][m][1]));
;                 }
.LBB0_1166:
	s_lshl_b32 s4, s15, 8
	v_add_u32_e32 v178, s4, v194
	s_add_i32 s4, s4, 0xffff0000
	s_lshr_b32 s4, s4, 12
	s_lshr_b32 s5, s15, 5
	s_add_i32 s4, s4, 8
	s_cmpk_lt_i32 s15, 0x100
	s_cselect_b32 s4, s5, s4
	s_mulk_i32 s4, 0x1800
	s_ashr_i32 s5, s4, 31
	s_lshl_b64 s[4:5], s[4:5], 2
	v_readlane_b32 s72, v254, 38
	v_lshl_or_b32 v162, s14, 8, v196
	s_add_u32 s4, s43, s4
	v_readlane_b32 s84, v254, 50
	v_readlane_b32 s85, v254, 51
	v_lshlrev_b32_e32 v80, 2, v162
	v_ashrrev_i32_e32 v163, 31, v162
	s_addc_u32 s5, s44, s5
	v_readlane_b32 s86, v254, 52
	v_readlane_b32 s87, v254, 53
	s_mov_b64 s[12:13], s[84:85]
	v_lshl_add_u32 v152, v178, 12, v80
	v_lshl_add_u64 v[180:181], v[162:163], 2, s[4:5]
	s_mov_b64 s[14:15], s[86:87]
	global_load_dwordx4 v[136:139], v[180:181], off
	global_load_dwordx4 v[140:143], v[180:181], off offset:16
	global_load_dwordx4 v[210:213], v152, s[14:15] nt
	global_load_dwordx4 v[214:217], v152, s[14:15] offset:16 nt
	v_add_u32_e32 v167, 0x10000, v152
	global_load_dwordx4 v[218:221], v167, s[14:15] nt
	global_load_dwordx4 v[222:225], v167, s[14:15] offset:16 nt
	v_add_u32_e32 v165, 0x20000, v152
	global_load_dwordx4 v[240:243], v165, s[14:15] nt
	global_load_dwordx4 v[244:247], v165, s[14:15] offset:16 nt
	v_add_u32_e32 v164, 0x10000, v152
	v_add_u32_e32 v166, 0x20000, v152
	v_add_u32_e32 v168, 0x30000, v152
	v_add_u32_e32 v170, 0x80000, v152
	v_add_u32_e32 v172, 0x90000, v152
	v_add_u32_e32 v174, 0xa0000, v152
	v_add_u32_e32 v176, 0xb0000, v152
	v_ashrrev_i32_e32 v179, 31, v178
	v_readlane_b32 s73, v254, 39
	v_readlane_b32 s74, v254, 40
	v_readlane_b32 s75, v254, 41
	v_readlane_b32 s76, v254, 42
	v_readlane_b32 s77, v254, 43
	v_readlane_b32 s78, v254, 44
	v_readlane_b32 s79, v254, 45
	v_readlane_b32 s80, v254, 46
	v_readlane_b32 s81, v254, 47
	v_readlane_b32 s82, v254, 48
	v_readlane_b32 s83, v254, 49
	s_waitcnt vmcnt(5)
	v_pk_fma_f32 v[6:7], v[6:7], v[138:139], v[212:213]
	v_pk_fma_f32 v[4:5], v[4:5], v[136:137], v[210:211]
	s_waitcnt vmcnt(4)
	v_pk_fma_f32 v[2:3], v[2:3], v[142:143], v[216:217]
	v_pk_fma_f32 v[0:1], v[0:1], v[140:141], v[214:215]
	v_add_u32_e32 v167, 0x30000, v152
	global_load_dwordx4 v[210:213], v167, s[14:15] nt
	global_load_dwordx4 v[214:217], v167, s[14:15] offset:16 nt
	s_nop 0
	s_waitcnt vmcnt(5)
	v_pk_fma_f32 v[14:15], v[14:15], v[138:139], v[220:221]
	v_pk_fma_f32 v[12:13], v[12:13], v[136:137], v[218:219]
	s_waitcnt vmcnt(4)
	v_pk_fma_f32 v[10:11], v[10:11], v[142:143], v[224:225]
	v_pk_fma_f32 v[8:9], v[8:9], v[140:141], v[222:223]
	v_add_u32_e32 v165, 0x80000, v152
	global_load_dwordx4 v[218:221], v165, s[14:15] nt
	global_load_dwordx4 v[222:225], v165, s[14:15] offset:16 nt
	s_nop 0
	s_waitcnt vmcnt(5)
	v_pk_fma_f32 v[22:23], v[22:23], v[138:139], v[242:243]
	v_pk_fma_f32 v[20:21], v[20:21], v[136:137], v[240:241]
	s_waitcnt vmcnt(4)
	v_pk_fma_f32 v[18:19], v[18:19], v[142:143], v[246:247]
	v_pk_fma_f32 v[16:17], v[16:17], v[140:141], v[244:245]
	v_add_u32_e32 v167, 0x90000, v152
	global_load_dwordx4 v[240:243], v167, s[14:15] nt
	global_load_dwordx4 v[244:247], v167, s[14:15] offset:16 nt
	s_nop 0
	s_waitcnt vmcnt(5)
	v_pk_fma_f32 v[34:35], v[34:35], v[138:139], v[212:213]
	v_pk_fma_f32 v[32:33], v[32:33], v[136:137], v[210:211]
	s_waitcnt vmcnt(4)
	v_pk_fma_f32 v[26:27], v[26:27], v[142:143], v[216:217]
	v_pk_fma_f32 v[24:25], v[24:25], v[140:141], v[214:215]
	v_add_u32_e32 v165, 0xa0000, v152
	global_load_dwordx4 v[210:213], v165, s[14:15] nt
	global_load_dwordx4 v[214:217], v165, s[14:15] offset:16 nt
	s_nop 0
	s_waitcnt vmcnt(5)
	v_pk_fma_f32 v[54:55], v[54:55], v[138:139], v[220:221]
	v_pk_fma_f32 v[52:53], v[52:53], v[136:137], v[218:219]
	s_waitcnt vmcnt(4)
	v_pk_fma_f32 v[46:47], v[46:47], v[142:143], v[224:225]
	v_pk_fma_f32 v[44:45], v[44:45], v[140:141], v[222:223]
	v_add_u32_e32 v167, 0xb0000, v152
	global_load_dwordx4 v[218:221], v167, s[14:15] nt
	global_load_dwordx4 v[222:225], v167, s[14:15] offset:16 nt
	s_nop 0
	s_waitcnt vmcnt(5)
	v_pk_fma_f32 v[74:75], v[74:75], v[138:139], v[242:243]
	v_pk_fma_f32 v[72:73], v[72:73], v[136:137], v[240:241]
	s_waitcnt vmcnt(4)
	v_pk_fma_f32 v[58:59], v[58:59], v[142:143], v[246:247]
	v_pk_fma_f32 v[56:57], v[56:57], v[140:141], v[244:245]
	global_load_dwordx4 v[240:243], v152, s[14:15] offset:128 nt
	global_load_dwordx4 v[244:247], v152, s[14:15] offset:144 nt
	s_nop 0
	s_waitcnt vmcnt(5)
	v_pk_fma_f32 v[90:91], v[70:71], v[138:139], v[212:213]
	v_pk_fma_f32 v[88:89], v[68:69], v[136:137], v[210:211]
	s_waitcnt vmcnt(4)
	v_pk_fma_f32 v[82:83], v[66:67], v[142:143], v[216:217]
	v_pk_fma_f32 v[80:81], v[64:65], v[140:141], v[214:215]
	v_add_u32_e32 v167, 0x10080, v152
	global_load_dwordx4 v[210:213], v167, s[14:15] nt
	global_load_dwordx4 v[214:217], v167, s[14:15] offset:16 nt
	s_nop 0
	s_waitcnt vmcnt(5)
	v_pk_fma_f32 v[66:67], v[38:39], v[138:139], v[220:221]
	v_pk_fma_f32 v[64:65], v[36:37], v[136:137], v[218:219]
	s_waitcnt vmcnt(4)
; template <int MODE> DI void epilogue(const Epi& E, f32x4 (&acc)[2][2][4][2], const Unit& u, int wr, int wc, int fr, int fq) {
;     ...
;             const f32x4 g0 = *(const f32x4*)(E.gt + bidx * 6144 + col0 + bj * 32), g1 = *(const f32x4*)(E.gt + bidx * 6144 + col0 + bj * 32 + 4);
; #pragma unroll
;             for (int ai = 0; ai < 2; ++ai)
; #pragma unroll
;                 for (int m = 0; m < 4; ++m) {
;                     const unsigned off = E1_OFF(ai, m, bj);
;                     const f32x4 b0 = __builtin_nontemporal_load((const f32x4*)(base + off)), b1 = __builtin_nontemporal_load((const f32x4*)(base + off + 16));
;                     acc[ai][bj][m][0] = b0 + g0 * acc[ai][bj][m][0];
;                     acc[ai][bj][m][1] = b1 + g1 * acc[ai][bj][m][1];
;                     asm volatile("" : "+v"(acc[ai][bj][m][0]), "+v"(acc[ai][bj][m][1]));
;                 }
;             asm volatile("" ::: "memory");
;         }
; #pragma unroll
;         for (int ai = 0; ai < 2; ++ai)
; #pragma unroll
;             for (int m = 0; m < 4; ++m) {
;                 float sq = 0.f;
; #pragma unroll
;                 for (int bj = 0; bj < 2; ++bj)
; #pragma unroll
;                     for (int n = 0; n < 2; ++n) { const f32x4 v = acc[ai][bj][m][n]; sq += (v.x * v.x + v.y * v.y) + (v.z * v.z + v.w * v.w); }
;                 sq += __shfl_xor(sq, 16); sq += __shfl_xor(sq, 32);
;                 if (fq == 0) __hip_atomic_fetch_add(E.rowq + row0 + ai * HALF + m * 16, (1ull << 52) + (unsigned long long)(sq * 65536.0f + 0.5f), __ATOMIC_RELAXED, __HIP_MEMORY_SCOPE_AGENT);
	v_pk_fma_f32 v[70:71], v[30:31], v[142:143], v[224:225]
	v_pk_fma_f32 v[68:69], v[28:29], v[140:141], v[222:223]
	v_add_u32_e32 v165, 0x20080, v152
	global_load_dwordx4 v[218:221], v165, s[14:15] nt
	global_load_dwordx4 v[222:225], v165, s[14:15] offset:16 nt
	s_nop 0
	global_load_dwordx4 v[140:143], v[180:181], off offset:128
	global_load_dwordx4 v[136:139], v[180:181], off offset:144
	v_add_u32_e32 v180, 0x10080, v152
	s_waitcnt vmcnt(1)
	v_pk_fma_f32 v[38:39], v[134:135], v[142:143], v[242:243]
	v_pk_fma_f32 v[36:37], v[132:133], v[140:141], v[240:241]
	s_waitcnt vmcnt(0)
	v_pk_fma_f32 v[30:31], v[130:131], v[138:139], v[246:247]
	v_pk_fma_f32 v[28:29], v[128:129], v[136:137], v[244:245]
	v_add_u32_e32 v167, 0x30080, v152
	global_load_dwordx4 v[240:243], v167, s[14:15] nt
	global_load_dwordx4 v[244:247], v167, s[14:15] offset:16 nt
	v_add_u32_e32 v130, 0x20080, v152
	v_mul_f32_e32 v131, v5, v5
	v_fmac_f32_e32 v131, v4, v4
	v_and_b32_e32 v129, 64, v200
	v_xor_b32_e32 v128, 16, v200
	v_add_u32_e32 v129, 64, v129
	v_cmp_lt_i32_e32 vcc, v128, v129
	v_pk_fma_f32 v[50:51], v[50:51], v[142:143], v[212:213]
	v_pk_fma_f32 v[48:49], v[48:49], v[140:141], v[210:211]
	v_pk_fma_f32 v[42:43], v[42:43], v[138:139], v[216:217]
	v_pk_fma_f32 v[40:41], v[40:41], v[136:137], v[214:215]
	v_add_u32_e32 v165, 0x80080, v152
	global_load_dwordx4 v[210:213], v165, s[14:15] nt
	global_load_dwordx4 v[214:217], v165, s[14:15] offset:16 nt
	v_add_u32_e32 v184, 0x30080, v152
	v_cndmask_b32_e32 v128, v200, v128, vcc
	v_lshlrev_b32_e32 v128, 2, v128
	v_pk_fma_f32 v[78:79], v[78:79], v[142:143], v[220:221]
	v_pk_fma_f32 v[76:77], v[76:77], v[140:141], v[218:219]
	v_pk_fma_f32 v[62:63], v[62:63], v[138:139], v[224:225]
	v_pk_fma_f32 v[60:61], v[60:61], v[136:137], v[222:223]
	v_add_u32_e32 v167, 0x90080, v152
	global_load_dwordx4 v[218:221], v167, s[14:15] nt
	global_load_dwordx4 v[222:225], v167, s[14:15] offset:16 nt
	v_add_u32_e32 v186, 0x80080, v152
	s_waitcnt vmcnt(5)
	v_pk_fma_f32 v[94:95], v[94:95], v[142:143], v[242:243]
	v_pk_fma_f32 v[92:93], v[92:93], v[140:141], v[240:241]
	s_waitcnt vmcnt(4)
	v_pk_fma_f32 v[86:87], v[86:87], v[138:139], v[246:247]
	v_pk_fma_f32 v[84:85], v[84:85], v[136:137], v[244:245]
	v_add_u32_e32 v165, 0xa0080, v152
	global_load_dwordx4 v[240:243], v165, s[14:15] nt
	global_load_dwordx4 v[244:247], v165, s[14:15] offset:16 nt
	v_add_u32_e32 v188, 0x90080, v152
	s_waitcnt vmcnt(5)
	v_pk_fma_f32 v[102:103], v[102:103], v[142:143], v[212:213]
	v_pk_fma_f32 v[100:101], v[100:101], v[140:141], v[210:211]
	s_waitcnt vmcnt(4)
	v_pk_fma_f32 v[98:99], v[98:99], v[138:139], v[216:217]
	v_pk_fma_f32 v[96:97], v[96:97], v[136:137], v[214:215]
	v_add_u32_e32 v167, 0xb0080, v152
	global_load_dwordx4 v[210:213], v167, s[14:15] nt
	global_load_dwordx4 v[214:217], v167, s[14:15] offset:16 nt
	v_add_u32_e32 v190, 0xa0080, v152
	v_add_u32_e32 v192, 0xb0080, v152
	s_waitcnt vmcnt(5)
	v_pk_fma_f32 v[110:111], v[110:111], v[142:143], v[220:221]
	v_pk_fma_f32 v[108:109], v[108:109], v[140:141], v[218:219]
	s_waitcnt vmcnt(4)
	v_pk_fma_f32 v[106:107], v[106:107], v[138:139], v[224:225]
	v_pk_fma_f32 v[104:105], v[104:105], v[136:137], v[222:223]
	s_nop 0
	s_waitcnt vmcnt(3)
	v_pk_fma_f32 v[118:119], v[118:119], v[142:143], v[242:243]
	v_pk_fma_f32 v[116:117], v[116:117], v[140:141], v[240:241]
	s_waitcnt vmcnt(2)
	v_pk_fma_f32 v[114:115], v[114:115], v[138:139], v[246:247]
	v_pk_fma_f32 v[112:113], v[112:113], v[136:137], v[244:245]
	v_mul_f32_e32 v132, v7, v7
	v_mul_f32_e32 v133, v1, v1
	v_mul_f32_e32 v134, v3, v3
	v_fmac_f32_e32 v132, v6, v6
	v_fmac_f32_e32 v133, v0, v0
	v_fmac_f32_e32 v134, v2, v2
	v_add_f32_e32 v131, v131, v132
	v_add_f32_e32 v132, v133, v134
	v_add_f32_e32 v131, v131, v132
	v_mul_f32_e32 v132, v37, v37
	v_mul_f32_e32 v133, v39, v39
	v_mul_f32_e32 v134, v29, v29
	v_mul_f32_e32 v135, v31, v31
	v_fmac_f32_e32 v132, v36, v36
	v_fmac_f32_e32 v133, v38, v38
	v_fmac_f32_e32 v134, v28, v28
	v_fmac_f32_e32 v135, v30, v30
	v_add_f32_e32 v132, v132, v133
	v_add_f32_e32 v133, v134, v135
	v_add_f32_e32 v131, v131, v132
	v_add_f32_e32 v131, v133, v131
	ds_bpermute_b32 v132, v128, v131
	v_xor_b32_e32 v133, 32, v200
	v_cmp_lt_i32_e32 vcc, v133, v129
	s_waitcnt lgkmcnt(0)
	v_add_f32_e32 v131, v131, v132
	v_cndmask_b32_e32 v129, v200, v133, vcc
	v_lshlrev_b32_e32 v129, 2, v129
	ds_bpermute_b32 v132, v129, v131
	s_waitcnt vmcnt(1)
	v_pk_fma_f32 v[126:127], v[126:127], v[142:143], v[212:213]
	v_pk_fma_f32 v[124:125], v[124:125], v[140:141], v[210:211]
	s_waitcnt vmcnt(0)
	v_pk_fma_f32 v[122:123], v[122:123], v[138:139], v[216:217]
	v_pk_fma_f32 v[120:121], v[120:121], v[136:137], v[214:215]
	v_lshl_add_u64 v[136:137], v[178:179], 3, s[18:19]
	s_and_saveexec_b64 s[4:5], s[0:1]
	s_cbranch_execz .LBB0_1168
	s_waitcnt lgkmcnt(0)
	v_add_f32_e32 v131, v131, v132
	v_fma_f32 v131, v131, s50, 0.5
	v_trunc_f32_e32 v131, v131
	v_mul_f32_e32 v132, 0x2f800000, v131
	v_floor_f32_e32 v132, v132
	v_fmac_f32_e32 v131, 0xcf800000, v132
	v_cvt_u32_f32_e32 v133, v132
	v_cvt_u32_f32_e32 v132, v131
	v_add_u32_e32 v133, 0x100000, v133
	global_atomic_add_x2 v[136:137], v[132:133], off
